# P0 adaLN GEMV inner loop: global loads issued earlier (register-renamed), vmcnt waits re-derived, so 4 loads instead of 2 are in flight at the first wait
# baseline (speedup 1.0000x reference)
.LBB0_19:
	global_load_dwordx4 v[2:5], v[48:49], off
	s_mov_b32 s2, 0xffe80000
	v_add_co_u32_e64 v28, s[2:3], s2, v48
	v_add_u32_e32 v74, 0x4000, v87
	v_add_u32_e32 v78, 0x8000, v87
	v_add_u32_e32 v80, 0xc000, v87
	v_add_u32_e32 v67, 0x10000, v87
	v_add_u32_e32 v69, 0x10008, v87
	v_add_u32_e32 v70, 0x10010, v87
	v_add_u32_e32 v71, 0x10018, v87
	v_add_u32_e32 v72, 0x10020, v87
	v_add_u32_e32 v73, 0x10028, v87
	v_add_u32_e32 v82, 0x10030, v87
	v_add_u32_e32 v81, 0x10038, v87
	v_add_u32_e32 v83, 0x10040, v87
	v_add_u32_e32 v84, 0x10048, v87
	v_add_u32_e32 v85, 0x10050, v87
	v_add_u32_e32 v86, 0x10058, v87
	v_add_u32_e32 v88, 0x10060, v87
	v_addc_co_u32_e64 v29, s[2:3], -1, v49, s[2:3]
	global_load_dwordx4 v[160:163], v[28:29], off
	ds_read2_b32 v[26:27], v87 offset1:2
	ds_read2_b32 v[56:57], v87 offset0:4 offset1:6
	ds_read2_b32 v[52:53], v87 offset0:8 offset1:10
	ds_read2_b32 v[50:51], v87 offset0:12 offset1:14
	ds_read2_b32 v[54:55], v87 offset0:16 offset1:18
	ds_read2_b32 v[58:59], v87 offset0:20 offset1:22
	ds_read2_b32 v[60:61], v87 offset0:24 offset1:26
	v_add_u32_e32 v89, 0x10068, v87
	ds_read2_b32 v[62:63], v87 offset0:28 offset1:30
	v_add_u32_e32 v97, 0x10070, v87
	v_add_u32_e32 v107, 0x10078, v87
	ds_read_b32 v158, v67
	ds_read2_b32 v[156:157], v74 offset1:2
	ds_read2_b32 v[154:155], v78 offset1:2
	ds_read2_b32 v[152:153], v80 offset1:2
	ds_read_b32 v150, v69
	ds_read_b32 v148, v70
	ds_read2_b32 v[146:147], v74 offset0:4 offset1:6
	ds_read2_b32 v[144:145], v78 offset0:4 offset1:6
	ds_read2_b32 v[142:143], v80 offset0:4 offset1:6
	ds_read_b32 v140, v71
	ds_read_b32 v138, v72
	ds_read2_b32 v[136:137], v74 offset0:8 offset1:10
	ds_read2_b32 v[132:133], v78 offset0:8 offset1:10
	ds_read2_b32 v[130:131], v80 offset0:8 offset1:10
	ds_read_b32 v128, v73
	ds_read_b32 v126, v82
	ds_read2_b32 v[120:121], v74 offset0:12 offset1:14
	ds_read2_b32 v[72:73], v78 offset0:12 offset1:14
	ds_read2_b32 v[70:71], v80 offset0:12 offset1:14
	ds_read_b32 v118, v81
	ds_read_b32 v116, v83
	ds_read2_b32 v[114:115], v74 offset0:16 offset1:18
	ds_read2_b32 v[112:113], v78 offset0:16 offset1:18
	ds_read2_b32 v[110:111], v80 offset0:16 offset1:18
	ds_read_b32 v108, v84
	ds_read_b32 v106, v85
	ds_read2_b32 v[104:105], v74 offset0:20 offset1:22
	ds_read2_b32 v[102:103], v78 offset0:20 offset1:22
	ds_read2_b32 v[100:101], v80 offset0:20 offset1:22
	ds_read_b32 v96, v86
	ds_read2_b32 v[94:95], v74 offset0:24 offset1:26
	ds_read2_b32 v[92:93], v78 offset0:24 offset1:26
	ds_read2_b32 v[90:91], v80 offset0:24 offset1:26
	ds_read_b32 v88, v88
	ds_read_b32 v86, v89
	ds_read2_b32 v[84:85], v74 offset0:28 offset1:30
	ds_read2_b32 v[82:83], v78 offset0:28 offset1:30
	ds_read2_b32 v[80:81], v80 offset0:28 offset1:30
	ds_read_b32 v78, v97
	ds_read_b32 v74, v107
	s_mov_b32 s4, 0xffeb0000
	v_add_co_u32_e64 v32, s[4:5], s4, v48
	s_mov_b32 s6, 0xffee0000
	s_nop 0
	v_addc_co_u32_e64 v33, s[2:3], -1, v49, s[4:5]
	global_load_dwordx4 v[188:191], v[32:33], off
	v_add_co_u32_e64 v30, s[6:7], s6, v48
	s_mov_b32 s8, 0xfff10000
	s_mov_b32 s10, 0xfff40000
	v_add_co_u32_e64 v34, s[8:9], s8, v48
	v_add_co_u32_e64 v36, s[10:11], s10, v48
	v_addc_co_u32_e64 v31, s[2:3], -1, v49, s[6:7]
	global_load_dwordx4 v[194:197], v[30:31], off
	v_addc_co_u32_e64 v35, s[2:3], -1, v49, s[8:9]
	v_addc_co_u32_e64 v37, s[2:3], -1, v49, s[10:11]
	s_mov_b32 s12, 0xfff70000
	v_add_co_u32_e64 v38, s[12:13], s12, v48
	s_mov_b32 s14, 0xfffa0000
	v_add_co_u32_e64 v40, s[14:15], s14, v48
	s_mov_b32 s16, 0xfffd0000
	v_addc_co_u32_e64 v39, s[2:3], -1, v49, s[12:13]
	v_add_co_u32_e64 v64, s[16:17], s16, v48
	v_addc_co_u32_e64 v41, s[2:3], -1, v49, s[14:15]
	s_mov_b32 s18, 0x30000
	v_addc_co_u32_e64 v65, s[2:3], -1, v49, s[16:17]
	v_add_co_u32_e64 v66, s[18:19], s18, v48
	s_mov_b32 s20, 0x60000
	s_nop 0
	v_addc_co_u32_e64 v67, s[2:3], 0, v49, s[18:19]
	v_add_co_u32_e64 v68, s[20:21], s20, v48
	s_mov_b32 s22, 0x90000
	s_mov_b32 s24, 0xc0000
	s_mov_b32 s26, 0xf0000
	v_add_co_u32_e64 v76, s[22:23], s22, v48
	v_add_co_u32_e64 v98, s[24:25], s24, v48
	v_add_co_u32_e64 v122, s[26:27], s26, v48
	v_addc_co_u32_e64 v69, s[2:3], 0, v49, s[20:21]
	s_mov_b32 s28, 0x120000
	v_addc_co_u32_e64 v77, s[2:3], 0, v49, s[22:23]
	v_addc_co_u32_e64 v99, s[2:3], 0, v49, s[24:25]
	v_addc_co_u32_e64 v123, s[2:3], 0, v49, s[26:27]
	v_add_co_u32_e64 v124, s[28:29], s28, v48
	s_mov_b32 s34, 0x150000
	v_add_co_u32_e64 v134, s[34:35], s34, v48
	v_addc_co_u32_e64 v125, s[2:3], 0, v49, s[28:29]
	s_nop 0
	v_addc_co_u32_e64 v135, s[2:3], 0, v49, s[34:35]
	v_add_u32_e32 v87, 0x80, v87
	s_add_i32 s53, s53, 32
	s_mov_b64 s[2:3], 0x300000
	v_lshl_add_u64 v[48:49], v[48:49], 0, s[2:3]
	s_cmpk_gt_u32 s53, 0x1fd
	s_waitcnt lgkmcnt(14)
	s_waitcnt vmcnt(0)
	v_pk_fma_f32 v[28:29], v[162:163], v[158:159], v[24:25] op_sel_hi:[1,0,1]
	v_pk_fma_f32 v[166:167], v[160:161], v[158:159], v[22:23] op_sel_hi:[1,0,1]
	v_pk_fma_f32 v[8:9], v[162:163], v[26:27], v[8:9] op_sel_hi:[1,0,1]
	v_pk_fma_f32 v[6:7], v[160:161], v[26:27], v[6:7] op_sel_hi:[1,0,1]
	v_pk_fma_f32 v[12:13], v[162:163], v[156:157], v[12:13] op_sel_hi:[1,0,1]
	v_pk_fma_f32 v[10:11], v[160:161], v[156:157], v[10:11] op_sel_hi:[1,0,1]
	v_pk_fma_f32 v[16:17], v[162:163], v[154:155], v[16:17] op_sel_hi:[1,0,1]
	v_pk_fma_f32 v[14:15], v[160:161], v[154:155], v[14:15] op_sel_hi:[1,0,1]
	v_pk_fma_f32 v[32:33], v[162:163], v[152:153], v[20:21] op_sel_hi:[1,0,1]
	v_pk_fma_f32 v[174:175], v[160:161], v[152:153], v[18:19] op_sel_hi:[1,0,1]
	global_load_dwordx4 v[158:161], v[34:35], off
	global_load_dwordx4 v[162:165], v[36:37], off
	global_load_dwordx4 v[170:173], v[38:39], off
	global_load_dwordx4 v[34:37], v[40:41], off
	global_load_dwordx4 v[38:41], v[64:65], off
	global_load_dwordx4 v[202:205], v[66:67], off
	global_load_dwordx4 v[206:209], v[68:69], off
	global_load_dwordx4 v[212:215], v[76:77], off
	global_load_dwordx4 v[220:223], v[98:99], off
	global_load_dwordx4 v[224:227], v[122:123], off
	global_load_dwordx4 v[18:21], v[124:125], off
	global_load_dwordx4 v[22:25], v[134:135], off
	v_mov_b32_e32 v26, v27
	v_pk_fma_f32 v[178:179], v[188:189], v[26:27], v[6:7] op_sel_hi:[1,0,1]
	v_mov_b32_e32 v6, v157
	v_pk_fma_f32 v[156:157], v[190:191], v[6:7], v[12:13] op_sel_hi:[1,0,1]
	v_pk_fma_f32 v[180:181], v[188:189], v[6:7], v[10:11] op_sel_hi:[1,0,1]
	v_mov_b32_e32 v6, v155
	v_pk_fma_f32 v[154:155], v[190:191], v[6:7], v[16:17] op_sel_hi:[1,0,1]
	v_pk_fma_f32 v[182:183], v[188:189], v[6:7], v[14:15] op_sel_hi:[1,0,1]
	v_mov_b32_e32 v6, v153
	v_pk_fma_f32 v[64:65], v[190:191], v[6:7], v[32:33] op_sel_hi:[1,0,1]
	v_pk_fma_f32 v[176:177], v[190:191], v[26:27], v[8:9] op_sel_hi:[1,0,1]
	v_pk_fma_f32 v[152:153], v[188:189], v[6:7], v[174:175] op_sel_hi:[1,0,1]
	v_pk_fma_f32 v[6:7], v[190:191], v[150:151], v[28:29] op_sel_hi:[1,0,1]
	v_pk_fma_f32 v[8:9], v[188:189], v[150:151], v[166:167] op_sel_hi:[1,0,1]
	v_pk_fma_f32 v[98:99], v[196:197], v[148:149], v[6:7] op_sel_hi:[1,0,1]
	v_pk_fma_f32 v[148:149], v[194:195], v[148:149], v[8:9] op_sel_hi:[1,0,1]
	v_pk_fma_f32 v[66:67], v[196:197], v[56:57], v[176:177] op_sel_hi:[1,0,1]
	v_pk_fma_f32 v[68:69], v[194:195], v[56:57], v[178:179] op_sel_hi:[1,0,1]
	v_pk_fma_f32 v[76:77], v[196:197], v[146:147], v[156:157] op_sel_hi:[1,0,1]
	v_pk_fma_f32 v[122:123], v[194:195], v[146:147], v[180:181] op_sel_hi:[1,0,1]
	v_pk_fma_f32 v[150:151], v[196:197], v[144:145], v[154:155] op_sel_hi:[1,0,1]
	v_pk_fma_f32 v[154:155], v[194:195], v[144:145], v[182:183] op_sel_hi:[1,0,1]
	v_pk_fma_f32 v[64:65], v[196:197], v[142:143], v[64:65] op_sel_hi:[1,0,1]
	v_pk_fma_f32 v[152:153], v[194:195], v[142:143], v[152:153] op_sel_hi:[1,0,1]
	v_mov_b32_e32 v56, v57
	s_waitcnt vmcnt(11)
	v_pk_fma_f32 v[124:125], v[160:161], v[56:57], v[66:67] op_sel_hi:[1,0,1]
	v_pk_fma_f32 v[134:135], v[158:159], v[56:57], v[68:69] op_sel_hi:[1,0,1]
	v_mov_b32_e32 v56, v147
	v_pk_fma_f32 v[146:147], v[160:161], v[56:57], v[76:77] op_sel_hi:[1,0,1]
	v_pk_fma_f32 v[122:123], v[158:159], v[56:57], v[122:123] op_sel_hi:[1,0,1]
	v_mov_b32_e32 v56, v145
	v_pk_fma_f32 v[144:145], v[160:161], v[56:57], v[150:151] op_sel_hi:[1,0,1]
	v_pk_fma_f32 v[150:151], v[158:159], v[56:57], v[154:155] op_sel_hi:[1,0,1]
	v_mov_b32_e32 v56, v143
	v_pk_fma_f32 v[154:155], v[160:161], v[56:57], v[64:65] op_sel_hi:[1,0,1]
	v_pk_fma_f32 v[152:153], v[158:159], v[56:57], v[152:153] op_sel_hi:[1,0,1]
	v_pk_fma_f32 v[98:99], v[160:161], v[140:141], v[98:99] op_sel_hi:[1,0,1]
	v_pk_fma_f32 v[140:141], v[158:159], v[140:141], v[148:149] op_sel_hi:[1,0,1]
	v_mov_b32_e32 v142, v53
	v_mov_b32_e32 v148, v137
	s_waitcnt vmcnt(10)
	v_pk_fma_f32 v[98:99], v[164:165], v[138:139], v[98:99] op_sel_hi:[1,0,1]
	v_pk_fma_f32 v[138:139], v[162:163], v[138:139], v[140:141] op_sel_hi:[1,0,1]
	v_mov_b32_e32 v140, v133
	v_pk_fma_f32 v[124:125], v[164:165], v[52:53], v[124:125] op_sel_hi:[1,0,1]
	v_pk_fma_f32 v[52:53], v[162:163], v[52:53], v[134:135] op_sel_hi:[1,0,1]
	v_mov_b32_e32 v134, v131
	v_pk_fma_f32 v[146:147], v[164:165], v[136:137], v[146:147] op_sel_hi:[1,0,1]
	v_pk_fma_f32 v[122:123], v[162:163], v[136:137], v[122:123] op_sel_hi:[1,0,1]
	v_pk_fma_f32 v[144:145], v[164:165], v[132:133], v[144:145] op_sel_hi:[1,0,1]
	v_pk_fma_f32 v[132:133], v[162:163], v[132:133], v[150:151] op_sel_hi:[1,0,1]
	v_pk_fma_f32 v[154:155], v[164:165], v[130:131], v[154:155] op_sel_hi:[1,0,1]
	v_pk_fma_f32 v[130:131], v[162:163], v[130:131], v[152:153] op_sel_hi:[1,0,1]
	s_waitcnt vmcnt(9)
	v_pk_fma_f32 v[124:125], v[172:173], v[142:143], v[124:125] op_sel_hi:[1,0,1]
	v_pk_fma_f32 v[52:53], v[170:171], v[142:143], v[52:53] op_sel_hi:[1,0,1]
	v_pk_fma_f32 v[146:147], v[172:173], v[148:149], v[146:147] op_sel_hi:[1,0,1]
	v_pk_fma_f32 v[122:123], v[170:171], v[148:149], v[122:123] op_sel_hi:[1,0,1]
	v_pk_fma_f32 v[144:145], v[172:173], v[140:141], v[144:145] op_sel_hi:[1,0,1]
	v_pk_fma_f32 v[132:133], v[170:171], v[140:141], v[132:133] op_sel_hi:[1,0,1]
	v_pk_fma_f32 v[154:155], v[172:173], v[134:135], v[154:155] op_sel_hi:[1,0,1]
	v_pk_fma_f32 v[130:131], v[170:171], v[134:135], v[130:131] op_sel_hi:[1,0,1]
	v_pk_fma_f32 v[98:99], v[172:173], v[128:129], v[98:99] op_sel_hi:[1,0,1]
	v_pk_fma_f32 v[128:129], v[170:171], v[128:129], v[138:139] op_sel_hi:[1,0,1]
	v_mov_b32_e32 v76, v51
	v_mov_b32_e32 v136, v121
	v_mov_b32_e32 v150, v73
	v_mov_b32_e32 v152, v71
	s_waitcnt vmcnt(8)
	v_pk_fma_f32 v[98:99], v[36:37], v[126:127], v[98:99] op_sel_hi:[1,0,1]
	v_pk_fma_f32 v[126:127], v[34:35], v[126:127], v[128:129] op_sel_hi:[1,0,1]
	v_pk_fma_f32 v[124:125], v[36:37], v[50:51], v[124:125] op_sel_hi:[1,0,1]
	v_pk_fma_f32 v[50:51], v[34:35], v[50:51], v[52:53] op_sel_hi:[1,0,1]
	v_pk_fma_f32 v[146:147], v[36:37], v[120:121], v[146:147] op_sel_hi:[1,0,1]
	v_pk_fma_f32 v[120:121], v[34:35], v[120:121], v[122:123] op_sel_hi:[1,0,1]
	v_pk_fma_f32 v[144:145], v[36:37], v[72:73], v[144:145] op_sel_hi:[1,0,1]
	v_pk_fma_f32 v[72:73], v[34:35], v[72:73], v[132:133] op_sel_hi:[1,0,1]
	v_pk_fma_f32 v[36:37], v[36:37], v[70:71], v[154:155] op_sel_hi:[1,0,1]
	v_pk_fma_f32 v[34:35], v[34:35], v[70:71], v[130:131] op_sel_hi:[1,0,1]
	v_mov_b32_e32 v68, v55
	v_mov_b32_e32 v156, v115
	v_mov_b32_e32 v158, v113
	v_mov_b32_e32 v142, v111
	v_mov_b32_e32 v66, v59
	s_waitcnt vmcnt(7)
	v_pk_fma_f32 v[70:71], v[40:41], v[76:77], v[124:125] op_sel_hi:[1,0,1]
	v_pk_fma_f32 v[50:51], v[38:39], v[76:77], v[50:51] op_sel_hi:[1,0,1]
	v_pk_fma_f32 v[76:77], v[40:41], v[136:137], v[146:147] op_sel_hi:[1,0,1]
	v_pk_fma_f32 v[120:121], v[38:39], v[136:137], v[120:121] op_sel_hi:[1,0,1]
	v_pk_fma_f32 v[124:125], v[40:41], v[150:151], v[144:145] op_sel_hi:[1,0,1]
	v_pk_fma_f32 v[72:73], v[38:39], v[150:151], v[72:73] op_sel_hi:[1,0,1]
	v_pk_fma_f32 v[36:37], v[40:41], v[152:153], v[36:37] op_sel_hi:[1,0,1]
	v_pk_fma_f32 v[34:35], v[38:39], v[152:153], v[34:35] op_sel_hi:[1,0,1]
	v_pk_fma_f32 v[40:41], v[40:41], v[118:119], v[98:99] op_sel_hi:[1,0,1]
	v_pk_fma_f32 v[38:39], v[38:39], v[118:119], v[126:127] op_sel_hi:[1,0,1]
	v_pk_fma_f32 v[40:41], v[4:5], v[116:117], v[40:41] op_sel_hi:[1,0,1]
	v_pk_fma_f32 v[38:39], v[2:3], v[116:117], v[38:39] op_sel_hi:[1,0,1]
	v_pk_fma_f32 v[70:71], v[4:5], v[54:55], v[70:71] op_sel_hi:[1,0,1]
	v_pk_fma_f32 v[50:51], v[2:3], v[54:55], v[50:51] op_sel_hi:[1,0,1]
	v_pk_fma_f32 v[54:55], v[4:5], v[114:115], v[76:77] op_sel_hi:[1,0,1]
	v_pk_fma_f32 v[76:77], v[2:3], v[114:115], v[120:121] op_sel_hi:[1,0,1]
	v_pk_fma_f32 v[98:99], v[4:5], v[112:113], v[124:125] op_sel_hi:[1,0,1]
	v_pk_fma_f32 v[72:73], v[2:3], v[112:113], v[72:73] op_sel_hi:[1,0,1]
	v_pk_fma_f32 v[4:5], v[4:5], v[110:111], v[36:37] op_sel_hi:[1,0,1]
	v_pk_fma_f32 v[2:3], v[2:3], v[110:111], v[34:35] op_sel_hi:[1,0,1]
	s_waitcnt vmcnt(6)
	v_pk_fma_f32 v[34:35], v[204:205], v[68:69], v[70:71] op_sel_hi:[1,0,1]
	v_pk_fma_f32 v[36:37], v[202:203], v[68:69], v[50:51] op_sel_hi:[1,0,1]
	v_pk_fma_f32 v[50:51], v[204:205], v[156:157], v[54:55] op_sel_hi:[1,0,1]
	v_pk_fma_f32 v[54:55], v[202:203], v[156:157], v[76:77] op_sel_hi:[1,0,1]
	v_pk_fma_f32 v[68:69], v[204:205], v[158:159], v[98:99] op_sel_hi:[1,0,1]
	v_pk_fma_f32 v[70:71], v[202:203], v[158:159], v[72:73] op_sel_hi:[1,0,1]
	v_pk_fma_f32 v[4:5], v[204:205], v[142:143], v[4:5] op_sel_hi:[1,0,1]
	v_pk_fma_f32 v[2:3], v[202:203], v[142:143], v[2:3] op_sel_hi:[1,0,1]
	v_pk_fma_f32 v[204:205], v[204:205], v[108:109], v[40:41] op_sel_hi:[1,0,1]
	v_pk_fma_f32 v[202:203], v[202:203], v[108:109], v[38:39] op_sel_hi:[1,0,1]
	s_waitcnt lgkmcnt(13)
	v_mov_b32_e32 v148, v105
	s_waitcnt lgkmcnt(12)
	v_mov_b32_e32 v140, v103
	s_waitcnt lgkmcnt(11)
	v_mov_b32_e32 v134, v101
	s_waitcnt vmcnt(5)
	v_pk_fma_f32 v[204:205], v[208:209], v[106:107], v[204:205] op_sel_hi:[1,0,1]
	v_pk_fma_f32 v[202:203], v[206:207], v[106:107], v[202:203] op_sel_hi:[1,0,1]
	v_pk_fma_f32 v[34:35], v[208:209], v[58:59], v[34:35] op_sel_hi:[1,0,1]
	v_pk_fma_f32 v[36:37], v[206:207], v[58:59], v[36:37] op_sel_hi:[1,0,1]
	v_pk_fma_f32 v[38:39], v[208:209], v[104:105], v[50:51] op_sel_hi:[1,0,1]
	v_pk_fma_f32 v[40:41], v[206:207], v[104:105], v[54:55] op_sel_hi:[1,0,1]
	v_pk_fma_f32 v[50:51], v[208:209], v[102:103], v[68:69] op_sel_hi:[1,0,1]
	v_pk_fma_f32 v[54:55], v[206:207], v[102:103], v[70:71] op_sel_hi:[1,0,1]
	v_pk_fma_f32 v[4:5], v[208:209], v[100:101], v[4:5] op_sel_hi:[1,0,1]
	v_pk_fma_f32 v[2:3], v[206:207], v[100:101], v[2:3] op_sel_hi:[1,0,1]
	s_waitcnt vmcnt(4)
	v_pk_fma_f32 v[26:27], v[214:215], v[66:67], v[34:35] op_sel_hi:[1,0,1]
	v_pk_fma_f32 v[28:29], v[212:213], v[66:67], v[36:37] op_sel_hi:[1,0,1]
	v_pk_fma_f32 v[34:35], v[214:215], v[148:149], v[38:39] op_sel_hi:[1,0,1]
	v_pk_fma_f32 v[36:37], v[212:213], v[148:149], v[40:41] op_sel_hi:[1,0,1]
	v_pk_fma_f32 v[38:39], v[214:215], v[140:141], v[50:51] op_sel_hi:[1,0,1]
	v_pk_fma_f32 v[40:41], v[212:213], v[140:141], v[54:55] op_sel_hi:[1,0,1]
	v_pk_fma_f32 v[4:5], v[214:215], v[134:135], v[4:5] op_sel_hi:[1,0,1]
	v_pk_fma_f32 v[2:3], v[212:213], v[134:135], v[2:3] op_sel_hi:[1,0,1]
	s_waitcnt lgkmcnt(10)
	v_pk_fma_f32 v[214:215], v[214:215], v[96:97], v[204:205] op_sel_hi:[1,0,1]
	v_pk_fma_f32 v[212:213], v[212:213], v[96:97], v[202:203] op_sel_hi:[1,0,1]
	v_mov_b32_e32 v64, v61
	s_waitcnt lgkmcnt(9)
	v_mov_b32_e32 v138, v95
	s_waitcnt lgkmcnt(8)
	v_mov_b32_e32 v160, v93
	s_waitcnt lgkmcnt(7)
	v_mov_b32_e32 v162, v91
	s_waitcnt vmcnt(3)
	v_pk_fma_f32 v[26:27], v[222:223], v[60:61], v[26:27] op_sel_hi:[1,0,1]
	v_pk_fma_f32 v[28:29], v[220:221], v[60:61], v[28:29] op_sel_hi:[1,0,1]
	v_pk_fma_f32 v[30:31], v[222:223], v[94:95], v[34:35] op_sel_hi:[1,0,1]
	v_pk_fma_f32 v[32:33], v[220:221], v[94:95], v[36:37] op_sel_hi:[1,0,1]
	v_pk_fma_f32 v[34:35], v[222:223], v[92:93], v[38:39] op_sel_hi:[1,0,1]
	v_pk_fma_f32 v[36:37], v[220:221], v[92:93], v[40:41] op_sel_hi:[1,0,1]
	v_pk_fma_f32 v[4:5], v[222:223], v[90:91], v[4:5] op_sel_hi:[1,0,1]
	v_pk_fma_f32 v[2:3], v[220:221], v[90:91], v[2:3] op_sel_hi:[1,0,1]
	s_waitcnt lgkmcnt(6)
	v_pk_fma_f32 v[222:223], v[222:223], v[88:89], v[214:215] op_sel_hi:[1,0,1]
	v_pk_fma_f32 v[220:221], v[220:221], v[88:89], v[212:213] op_sel_hi:[1,0,1]
	s_waitcnt vmcnt(2)
	v_pk_fma_f32 v[14:15], v[226:227], v[64:65], v[26:27] op_sel_hi:[1,0,1]
	v_pk_fma_f32 v[16:17], v[224:225], v[64:65], v[28:29] op_sel_hi:[1,0,1]
	v_pk_fma_f32 v[26:27], v[226:227], v[138:139], v[30:31] op_sel_hi:[1,0,1]
	v_pk_fma_f32 v[28:29], v[224:225], v[138:139], v[32:33] op_sel_hi:[1,0,1]
	v_pk_fma_f32 v[30:31], v[226:227], v[160:161], v[34:35] op_sel_hi:[1,0,1]
	v_pk_fma_f32 v[32:33], v[224:225], v[160:161], v[36:37] op_sel_hi:[1,0,1]
	v_pk_fma_f32 v[4:5], v[226:227], v[162:163], v[4:5] op_sel_hi:[1,0,1]
	v_pk_fma_f32 v[2:3], v[224:225], v[162:163], v[2:3] op_sel_hi:[1,0,1]
	s_waitcnt lgkmcnt(5)
	v_pk_fma_f32 v[226:227], v[226:227], v[86:87], v[222:223] op_sel_hi:[1,0,1]
	v_pk_fma_f32 v[224:225], v[224:225], v[86:87], v[220:221] op_sel_hi:[1,0,1]
	v_mov_b32_e32 v56, v63
	s_waitcnt lgkmcnt(4)
	v_mov_b32_e32 v128, v85
	s_waitcnt lgkmcnt(3)
	v_mov_b32_e32 v52, v83
	s_waitcnt lgkmcnt(2)
	v_mov_b32_e32 v122, v81
	s_waitcnt vmcnt(1)
	v_pk_fma_f32 v[10:11], v[20:21], v[62:63], v[14:15] op_sel_hi:[1,0,1]
	v_pk_fma_f32 v[12:13], v[18:19], v[62:63], v[16:17] op_sel_hi:[1,0,1]
	v_pk_fma_f32 v[14:15], v[20:21], v[84:85], v[26:27] op_sel_hi:[1,0,1]
	v_pk_fma_f32 v[16:17], v[18:19], v[84:85], v[28:29] op_sel_hi:[1,0,1]
	v_pk_fma_f32 v[26:27], v[20:21], v[82:83], v[30:31] op_sel_hi:[1,0,1]
	v_pk_fma_f32 v[28:29], v[18:19], v[82:83], v[32:33] op_sel_hi:[1,0,1]
	v_pk_fma_f32 v[4:5], v[20:21], v[80:81], v[4:5] op_sel_hi:[1,0,1]
	v_pk_fma_f32 v[2:3], v[18:19], v[80:81], v[2:3] op_sel_hi:[1,0,1]
	s_waitcnt lgkmcnt(1)
	v_pk_fma_f32 v[30:31], v[20:21], v[78:79], v[226:227] op_sel_hi:[1,0,1]
	v_pk_fma_f32 v[32:33], v[18:19], v[78:79], v[224:225] op_sel_hi:[1,0,1]
	s_waitcnt vmcnt(0)
	v_pk_fma_f32 v[8:9], v[24:25], v[56:57], v[10:11] op_sel_hi:[1,0,1]
	v_pk_fma_f32 v[6:7], v[22:23], v[56:57], v[12:13] op_sel_hi:[1,0,1]
	v_pk_fma_f32 v[12:13], v[24:25], v[128:129], v[14:15] op_sel_hi:[1,0,1]
	v_pk_fma_f32 v[10:11], v[22:23], v[128:129], v[16:17] op_sel_hi:[1,0,1]
	v_pk_fma_f32 v[16:17], v[24:25], v[52:53], v[26:27] op_sel_hi:[1,0,1]
	v_pk_fma_f32 v[14:15], v[22:23], v[52:53], v[28:29] op_sel_hi:[1,0,1]
	v_pk_fma_f32 v[20:21], v[24:25], v[122:123], v[4:5] op_sel_hi:[1,0,1]
	v_pk_fma_f32 v[18:19], v[22:23], v[122:123], v[2:3] op_sel_hi:[1,0,1]
	s_waitcnt lgkmcnt(0)
	v_pk_fma_f32 v[24:25], v[24:25], v[74:75], v[30:31] op_sel_hi:[1,0,1]
	v_pk_fma_f32 v[22:23], v[22:23], v[74:75], v[32:33] op_sel_hi:[1,0,1]
	s_cbranch_scc0 .LBB0_19
	ds_write_b128 v43, v[6:9]
	ds_write_b128 v43, v[10:13] offset:384
	ds_write_b128 v43, v[14:17] offset:768
	ds_write_b128 v43, v[18:21] offset:1152
	ds_write_b128 v43, v[22:25] offset:1536
